# XCD-aware tile order also on ev_in (each XCD owns 12 row-tiles), on top of the lane-pair-packed version
# speedup vs baseline: 1.0040x; 1.0009x over previous
.LBB0_260:
	s_and_b32 s0, s23, 7
	s_bfe_u32 s1, s23, 0x60003
	s_lshr_b32 s2, s23, 9
	s_lshl_b32 s2, s2, 6
	s_add_u32 s1, s1, s2
	s_mul_hi_u32 s2, s1, 0xaaaaaaab
	s_lshr_b32 s2, s2, 3
	s_mul_i32 s3, s2, 12
	s_sub_u32 s1, s1, s3
	s_mul_i32 s0, s0, 12
	s_add_u32 s0, s0, s1
	s_lshl_b32 s13, s0, 7
	s_lshl_b32 s14, s2, 7
	s_mov_b32 s4, s2
	v_lshl_or_b32 v64, v183, 3, v191
	v_and_b32_e32 v65, 63, v64
	v_lshrrev_b32_e32 v66, 3, v65
	v_lshrrev_b32_e32 v67, 4, v65
	v_xor_b32_e32 v67, v67, v65
	v_and_b32_e32 v67, 7, v67
	v_lshlrev_b32_e32 v67, 4, v67
	s_movk_i32 s99, 0x800
	v_mad_u32_u24 v112, v66, s99, v67
	v_xor_b32_e32 v68, 64, v112
	v_add_u32_e32 v113, 0x3c00, v68
	v_add_u32_e32 v114, 0x7800, v112
	v_add_u32_e32 v115, 0xb400, v68
	v_add_u32_e32 v116, 0x10000, v112
	v_add_u32_e32 v117, 0x13c00, v68
	v_add_u32_e32 v118, 0x17800, v112
	v_add_u32_e32 v119, 0x1b400, v68
	v_and_b32_e32 v69, 31, v64
	v_bfe_u32 v70, v64, 5, 1
	v_bfe_u32 v71, v64, 1, 3
	v_xor_b32_e32 v71, v71, v70
	v_lshlrev_b32_e32 v71, 4, v71
	v_bfe_u32 v72, v64, 7, 1
	v_lshl_or_b32 v72, v72, 6, v69
	v_lshl_add_u32 v120, v72, 7, v71
	v_bfe_u32 v73, v64, 6, 1
	v_lshl_or_b32 v73, v73, 6, v69
	v_lshl_add_u32 v124, v73, 7, v71
	v_add_u32_e32 v124, 0x4000, v124
	v_xor_b32_e32 v121, 32, v120
	v_xor_b32_e32 v125, 32, v124
	v_xor_b32_e32 v122, 64, v120
	v_xor_b32_e32 v126, 64, v124
	v_xor_b32_e32 v123, 96, v120
	v_xor_b32_e32 v127, 96, v124
	v_lshrrev_b32_e32 v74, 6, v64
	s_nop 0
	v_readfirstlane_b32 s100, v74
	s_nop 3
	s_lshl_b32 s98, s100, 13
	s_mov_b32 s101, 0x0
	s_mov_b32 s99, s14
	s_cmp_lt_u32 s100, 2
	s_cmov_b32 s101, 0xb171900
	s_cmov_b32 s99, s13
	s_and_b32 s100, s100, 1
	s_lshl_b32 s100, s100, 6
	s_add_u32 s99, s99, s100
	s_mul_i32 s99, s99, 0x800
	s_add_u32 s99, s99, s101
	s_add_u32 s0, s90, s99
	s_addc_u32 s1, s91, 0
	v_readlane_b32 s99, v251, 0
	s_cmp_lg_u32 s99, 0
	s_cbranch_scc1 .Lg1_pref
	s_add_u32 m0, s98, 0x0
	s_nop 0
	global_load_lds_dwordx4 v112, s[0:1] offset:0
	global_load_lds_dwordx4 v113, s[0:1] offset:1024
	global_load_lds_dwordx4 v114, s[0:1] offset:2048
	global_load_lds_dwordx4 v115, s[0:1] offset:3072
	s_add_u32 m0, s98, 0x1000
	s_nop 0
	global_load_lds_dwordx4 v116, s[0:1] offset:0
	global_load_lds_dwordx4 v117, s[0:1] offset:1024
	global_load_lds_dwordx4 v118, s[0:1] offset:2048
	global_load_lds_dwordx4 v119, s[0:1] offset:3072
	s_add_u32 s0, s0, 0x80
	s_addc_u32 s1, s1, 0
	s_add_u32 m0, s98, 0x8000
	s_nop 0
	global_load_lds_dwordx4 v112, s[0:1] offset:0
	global_load_lds_dwordx4 v113, s[0:1] offset:1024
	global_load_lds_dwordx4 v114, s[0:1] offset:2048
	global_load_lds_dwordx4 v115, s[0:1] offset:3072
	s_add_u32 m0, s98, 0x9000
	s_nop 0
	global_load_lds_dwordx4 v116, s[0:1] offset:0
	global_load_lds_dwordx4 v117, s[0:1] offset:1024
	global_load_lds_dwordx4 v118, s[0:1] offset:2048
	global_load_lds_dwordx4 v119, s[0:1] offset:3072
	s_add_u32 s0, s0, 0x80
	s_addc_u32 s1, s1, 0
	s_mov_b32 s101, 0
	s_branch .Lg1_prol

.Lg1_loop:
	s_barrier
	ds_read_b128 v[64:67], v120 offset:0
	ds_read_b128 v[72:75], v124 offset:0
	ds_read_b128 v[76:79], v124 offset:4096
	ds_read_b128 v[68:71], v120 offset:4096
	ds_read_b128 v[80:83], v121 offset:0
	ds_read_b128 v[88:91], v125 offset:0
	ds_read_b128 v[92:95], v125 offset:4096
	ds_read_b128 v[84:87], v121 offset:4096
	s_waitcnt lgkmcnt(4)
	v_mfma_f32_32x32x16_bf16 v[48:63], v[64:67], v[72:75], v[48:63]
	ds_read_b128 v[96:99], v122 offset:0
	v_mfma_f32_32x32x16_bf16 v[16:31], v[64:67], v[76:79], v[16:31]
	ds_read_b128 v[104:107], v126 offset:0
	v_mfma_f32_32x32x16_bf16 v[32:47], v[68:71], v[72:75], v[32:47]
	ds_read_b128 v[108:111], v126 offset:4096
	v_mfma_f32_32x32x16_bf16 v[0:15], v[68:71], v[76:79], v[0:15]
	ds_read_b128 v[100:103], v122 offset:4096
	s_waitcnt lgkmcnt(4)
	v_mfma_f32_32x32x16_bf16 v[48:63], v[80:83], v[88:91], v[48:63]
	ds_read_b128 v[64:67], v123 offset:0
	v_mfma_f32_32x32x16_bf16 v[16:31], v[80:83], v[92:95], v[16:31]
	ds_read_b128 v[72:75], v127 offset:0
	v_mfma_f32_32x32x16_bf16 v[32:47], v[84:87], v[88:91], v[32:47]
	ds_read_b128 v[76:79], v127 offset:4096
	v_mfma_f32_32x32x16_bf16 v[0:15], v[84:87], v[92:95], v[0:15]
	ds_read_b128 v[68:71], v123 offset:4096
	s_waitcnt lgkmcnt(4)
	v_mfma_f32_32x32x16_bf16 v[48:63], v[96:99], v[104:107], v[48:63]
	v_mfma_f32_32x32x16_bf16 v[16:31], v[96:99], v[108:111], v[16:31]
	v_mfma_f32_32x32x16_bf16 v[32:47], v[100:103], v[104:107], v[32:47]
	v_mfma_f32_32x32x16_bf16 v[0:15], v[100:103], v[108:111], v[0:15]
	s_waitcnt lgkmcnt(0)
	v_mfma_f32_32x32x16_bf16 v[48:63], v[64:67], v[72:75], v[48:63]
	v_mfma_f32_32x32x16_bf16 v[16:31], v[64:67], v[76:79], v[16:31]
	v_mfma_f32_32x32x16_bf16 v[32:47], v[68:71], v[72:75], v[32:47]
	v_mfma_f32_32x32x16_bf16 v[0:15], v[68:71], v[76:79], v[0:15]
	s_barrier
	s_add_u32 m0, s98, 0x0
	s_nop 0
	global_load_lds_dwordx4 v112, s[0:1] offset:0
	global_load_lds_dwordx4 v113, s[0:1] offset:1024
	global_load_lds_dwordx4 v114, s[0:1] offset:2048
	global_load_lds_dwordx4 v115, s[0:1] offset:3072
	s_add_u32 m0, s98, 0x1000
	s_nop 0
	global_load_lds_dwordx4 v116, s[0:1] offset:0
	global_load_lds_dwordx4 v117, s[0:1] offset:1024
	global_load_lds_dwordx4 v118, s[0:1] offset:2048
	global_load_lds_dwordx4 v119, s[0:1] offset:3072
	s_add_u32 s0, s0, 0x80
	s_addc_u32 s1, s1, 0
	s_waitcnt vmcnt(8)
	s_barrier
	ds_read_b128 v[64:67], v120 offset:32768
	ds_read_b128 v[72:75], v124 offset:32768
	ds_read_b128 v[76:79], v124 offset:36864
	ds_read_b128 v[68:71], v120 offset:36864
	ds_read_b128 v[80:83], v121 offset:32768
	ds_read_b128 v[88:91], v125 offset:32768
	ds_read_b128 v[92:95], v125 offset:36864
	ds_read_b128 v[84:87], v121 offset:36864
	s_waitcnt lgkmcnt(4)
	v_mfma_f32_32x32x16_bf16 v[48:63], v[64:67], v[72:75], v[48:63]
	ds_read_b128 v[96:99], v122 offset:32768
	v_mfma_f32_32x32x16_bf16 v[16:31], v[64:67], v[76:79], v[16:31]
	ds_read_b128 v[104:107], v126 offset:32768
	v_mfma_f32_32x32x16_bf16 v[32:47], v[68:71], v[72:75], v[32:47]
	ds_read_b128 v[108:111], v126 offset:36864
	v_mfma_f32_32x32x16_bf16 v[0:15], v[68:71], v[76:79], v[0:15]
	ds_read_b128 v[100:103], v122 offset:36864
	s_waitcnt lgkmcnt(4)
	v_mfma_f32_32x32x16_bf16 v[48:63], v[80:83], v[88:91], v[48:63]
	ds_read_b128 v[64:67], v123 offset:32768
	v_mfma_f32_32x32x16_bf16 v[16:31], v[80:83], v[92:95], v[16:31]
	ds_read_b128 v[72:75], v127 offset:32768
	v_mfma_f32_32x32x16_bf16 v[32:47], v[84:87], v[88:91], v[32:47]
	ds_read_b128 v[76:79], v127 offset:36864
	v_mfma_f32_32x32x16_bf16 v[0:15], v[84:87], v[92:95], v[0:15]
	ds_read_b128 v[68:71], v123 offset:36864
	s_waitcnt lgkmcnt(4)
	v_mfma_f32_32x32x16_bf16 v[48:63], v[96:99], v[104:107], v[48:63]
	v_mfma_f32_32x32x16_bf16 v[16:31], v[96:99], v[108:111], v[16:31]
	v_mfma_f32_32x32x16_bf16 v[32:47], v[100:103], v[104:107], v[32:47]
	v_mfma_f32_32x32x16_bf16 v[0:15], v[100:103], v[108:111], v[0:15]
	s_waitcnt lgkmcnt(0)
	v_mfma_f32_32x32x16_bf16 v[48:63], v[64:67], v[72:75], v[48:63]
	v_mfma_f32_32x32x16_bf16 v[16:31], v[64:67], v[76:79], v[16:31]
	v_mfma_f32_32x32x16_bf16 v[32:47], v[68:71], v[72:75], v[32:47]
	v_mfma_f32_32x32x16_bf16 v[0:15], v[68:71], v[76:79], v[0:15]
	s_barrier
	s_add_u32 m0, s98, 0x8000
	s_nop 0
	global_load_lds_dwordx4 v112, s[0:1] offset:0
	global_load_lds_dwordx4 v113, s[0:1] offset:1024
	global_load_lds_dwordx4 v114, s[0:1] offset:2048
	global_load_lds_dwordx4 v115, s[0:1] offset:3072
	s_add_u32 m0, s98, 0x9000
	s_nop 0
	global_load_lds_dwordx4 v116, s[0:1] offset:0
	global_load_lds_dwordx4 v117, s[0:1] offset:1024
	global_load_lds_dwordx4 v118, s[0:1] offset:2048
	global_load_lds_dwordx4 v119, s[0:1] offset:3072
	s_add_u32 s0, s0, 0x80
	s_addc_u32 s1, s1, 0
	s_sub_u32 s2, s2, 1
	s_waitcnt vmcnt(8)
	s_cmp_lg_u32 s2, 0
	s_cbranch_scc1 .Lg1_loop
	s_barrier
	ds_read_b128 v[64:67], v120 offset:0
	ds_read_b128 v[72:75], v124 offset:0
	ds_read_b128 v[76:79], v124 offset:4096
	ds_read_b128 v[68:71], v120 offset:4096
	ds_read_b128 v[80:83], v121 offset:0
	ds_read_b128 v[88:91], v125 offset:0
	ds_read_b128 v[92:95], v125 offset:4096
	ds_read_b128 v[84:87], v121 offset:4096
	s_waitcnt lgkmcnt(4)
	v_mfma_f32_32x32x16_bf16 v[48:63], v[64:67], v[72:75], v[48:63]
	ds_read_b128 v[96:99], v122 offset:0
	v_mfma_f32_32x32x16_bf16 v[16:31], v[64:67], v[76:79], v[16:31]
	ds_read_b128 v[104:107], v126 offset:0
	v_mfma_f32_32x32x16_bf16 v[32:47], v[68:71], v[72:75], v[32:47]
	ds_read_b128 v[108:111], v126 offset:4096
	v_mfma_f32_32x32x16_bf16 v[0:15], v[68:71], v[76:79], v[0:15]
	ds_read_b128 v[100:103], v122 offset:4096
	s_waitcnt lgkmcnt(4)
	v_mfma_f32_32x32x16_bf16 v[48:63], v[80:83], v[88:91], v[48:63]
	ds_read_b128 v[64:67], v123 offset:0
	v_mfma_f32_32x32x16_bf16 v[16:31], v[80:83], v[92:95], v[16:31]
	ds_read_b128 v[72:75], v127 offset:0
	v_mfma_f32_32x32x16_bf16 v[32:47], v[84:87], v[88:91], v[32:47]
	ds_read_b128 v[76:79], v127 offset:4096
	v_mfma_f32_32x32x16_bf16 v[0:15], v[84:87], v[92:95], v[0:15]
	ds_read_b128 v[68:71], v123 offset:4096
	s_waitcnt lgkmcnt(4)
	v_mfma_f32_32x32x16_bf16 v[48:63], v[96:99], v[104:107], v[48:63]
	v_mfma_f32_32x32x16_bf16 v[16:31], v[96:99], v[108:111], v[16:31]
	v_mfma_f32_32x32x16_bf16 v[32:47], v[100:103], v[104:107], v[32:47]
	v_mfma_f32_32x32x16_bf16 v[0:15], v[100:103], v[108:111], v[0:15]
	s_waitcnt lgkmcnt(0)
	v_mfma_f32_32x32x16_bf16 v[48:63], v[64:67], v[72:75], v[48:63]
	v_mfma_f32_32x32x16_bf16 v[16:31], v[64:67], v[76:79], v[16:31]
	v_mfma_f32_32x32x16_bf16 v[32:47], v[68:71], v[72:75], v[32:47]
	v_mfma_f32_32x32x16_bf16 v[0:15], v[68:71], v[76:79], v[0:15]
	s_barrier
	s_add_i32 s99, s23, s92
	s_mov_b32 s2, 0
	s_cmp_gt_i32 s99, 0xddf
	s_cbranch_scc1 .Lg1_nonext
	s_and_b32 s100, s99, 7
	s_bfe_u32 s101, s99, 0x60003
	s_lshr_b32 s99, s99, 9
	s_lshl_b32 s99, s99, 6
	s_add_u32 s101, s101, s99
	s_mul_hi_u32 s99, s101, 0xaaaaaaab
	s_lshr_b32 s99, s99, 3
	s_mul_i32 s2, s99, 12
	s_sub_u32 s101, s101, s2
	s_mul_i32 s100, s100, 12
	s_add_u32 s100, s100, s101
	s_lshl_b32 s100, s100, 7
	s_lshl_b32 s99, s99, 7
	s_sub_i32 s100, s100, s13
	s_sub_i32 s99, s99, s14
	s_lshr_b32 s2, s98, 13
	s_cmp_lt_u32 s2, 2
	s_cselect_b32 s2, s100, s99
	s_mul_i32 s2, s2, 0x800
	s_sub_i32 s2, s2, 0x800
	s_ashr_i32 s100, s2, 31
	s_add_u32 s0, s0, s2
	s_addc_u32 s1, s1, s100
	s_add_u32 m0, s98, 0x0
	s_nop 0
	global_load_lds_dwordx4 v112, s[0:1] offset:0
	global_load_lds_dwordx4 v113, s[0:1] offset:1024
	global_load_lds_dwordx4 v114, s[0:1] offset:2048
	global_load_lds_dwordx4 v115, s[0:1] offset:3072
	s_add_u32 m0, s98, 0x1000
	s_nop 0
	global_load_lds_dwordx4 v116, s[0:1] offset:0
	global_load_lds_dwordx4 v117, s[0:1] offset:1024
	global_load_lds_dwordx4 v118, s[0:1] offset:2048
	global_load_lds_dwordx4 v119, s[0:1] offset:3072
	s_add_u32 s0, s0, 0x80
	s_addc_u32 s1, s1, 0
	s_mov_b32 s2, 1
